# final RMSNorm: 4 rows per trip, 12 loads in flight with counted waits
# baseline (speedup 1.0000x reference)
.Lfn_head:
	s_mul_i32 s0, s12, 3
	s_add_i32 s0, s0, s10
	s_cmp_lt_i32 s0, 0x8000
	s_cbranch_scc0 .LBB0_814
	v_mov_b32_e32 v64, 0
	s_mov_b64 exec, vcc
	global_load_dword v64, v[16:17], off
	s_mov_b64 exec, -1
	v_lshl_add_u64 v[16:17], v[16:17], 0, s[14:15]
	v_mov_b32_e32 v65, 0
	s_mov_b64 exec, vcc
	global_load_dword v65, v[16:17], off
	s_mov_b64 exec, -1
	v_lshl_add_u64 v[16:17], v[16:17], 0, s[14:15]
	v_mov_b32_e32 v66, 0
	s_mov_b64 exec, vcc
	global_load_dword v66, v[16:17], off
	s_mov_b64 exec, -1
	v_lshl_add_u64 v[16:17], v[16:17], 0, s[14:15]
	v_mov_b32_e32 v67, 0
	s_mov_b64 exec, vcc
	global_load_dword v67, v[16:17], off
	s_mov_b64 exec, -1
	v_lshl_add_u64 v[16:17], v[16:17], 0, s[14:15]
	global_load_dwordx4 v[72:75], v[18:19], off
	global_load_dwordx4 v[76:79], v[18:19], off offset:1024
	v_lshl_add_u64 v[18:19], v[18:19], 0, s[2:3]
	global_load_dwordx4 v[80:83], v[18:19], off
	global_load_dwordx4 v[84:87], v[18:19], off offset:1024
	v_lshl_add_u64 v[18:19], v[18:19], 0, s[2:3]
	global_load_dwordx4 v[88:91], v[18:19], off
	global_load_dwordx4 v[92:95], v[18:19], off offset:1024
	v_lshl_add_u64 v[18:19], v[18:19], 0, s[2:3]
	global_load_dwordx4 v[96:99], v[18:19], off
	global_load_dwordx4 v[100:103], v[18:19], off offset:1024
	v_lshl_add_u64 v[18:19], v[18:19], 0, s[2:3]
	s_waitcnt vmcnt(8)
	ds_bpermute_b32 v68, v22, v64
	ds_bpermute_b32 v69, v22, v65
	ds_bpermute_b32 v70, v22, v66
	ds_bpermute_b32 v71, v22, v67
	s_waitcnt lgkmcnt(3)
	v_add_f32_e32 v64, v64, v68
	s_waitcnt lgkmcnt(2)
	v_add_f32_e32 v65, v65, v69
	s_waitcnt lgkmcnt(1)
	v_add_f32_e32 v66, v66, v70
	s_waitcnt lgkmcnt(0)
	v_add_f32_e32 v67, v67, v71
	ds_bpermute_b32 v68, v23, v64
	ds_bpermute_b32 v69, v23, v65
	ds_bpermute_b32 v70, v23, v66
	ds_bpermute_b32 v71, v23, v67
	s_waitcnt lgkmcnt(3)
	v_add_f32_e32 v64, v64, v68
	s_waitcnt lgkmcnt(2)
	v_add_f32_e32 v65, v65, v69
	s_waitcnt lgkmcnt(1)
	v_add_f32_e32 v66, v66, v70
	s_waitcnt lgkmcnt(0)
	v_add_f32_e32 v67, v67, v71
	ds_bpermute_b32 v68, v24, v64
	ds_bpermute_b32 v69, v24, v65
	ds_bpermute_b32 v70, v24, v66
	ds_bpermute_b32 v71, v24, v67
	s_waitcnt lgkmcnt(3)
	v_add_f32_e32 v64, v64, v68
	s_waitcnt lgkmcnt(2)
	v_add_f32_e32 v65, v65, v69
	s_waitcnt lgkmcnt(1)
	v_add_f32_e32 v66, v66, v70
	s_waitcnt lgkmcnt(0)
	v_add_f32_e32 v67, v67, v71
	ds_bpermute_b32 v68, v25, v64
	ds_bpermute_b32 v69, v25, v65
	ds_bpermute_b32 v70, v25, v66
	ds_bpermute_b32 v71, v25, v67
	s_waitcnt lgkmcnt(3)
	v_add_f32_e32 v64, v64, v68
	s_waitcnt lgkmcnt(2)
	v_add_f32_e32 v65, v65, v69
	s_waitcnt lgkmcnt(1)
	v_add_f32_e32 v66, v66, v70
	s_waitcnt lgkmcnt(0)
	v_add_f32_e32 v67, v67, v71
	ds_bpermute_b32 v68, v26, v64
	ds_bpermute_b32 v69, v26, v65
	ds_bpermute_b32 v70, v26, v66
	ds_bpermute_b32 v71, v26, v67
	s_waitcnt lgkmcnt(3)
	v_add_f32_e32 v64, v64, v68
	s_waitcnt lgkmcnt(2)
	v_add_f32_e32 v65, v65, v69
	s_waitcnt lgkmcnt(1)
	v_add_f32_e32 v66, v66, v70
	s_waitcnt lgkmcnt(0)
	v_add_f32_e32 v67, v67, v71
	ds_bpermute_b32 v68, v27, v64
	ds_bpermute_b32 v69, v27, v65
	ds_bpermute_b32 v70, v27, v66
	ds_bpermute_b32 v71, v27, v67
	s_waitcnt lgkmcnt(3)
	v_add_f32_e32 v64, v64, v68
	s_waitcnt lgkmcnt(2)
	v_add_f32_e32 v65, v65, v69
	s_waitcnt lgkmcnt(1)
	v_add_f32_e32 v66, v66, v70
	s_waitcnt lgkmcnt(0)
	v_add_f32_e32 v67, v67, v71
	v_fmamk_f32 v64, v64, 0x3a800000, v28
	v_fmamk_f32 v65, v65, 0x3a800000, v28
	v_fmamk_f32 v66, v66, 0x3a800000, v28
	v_fmamk_f32 v67, v67, 0x3a800000, v28
	v_rsq_f32_e32 v104, v64
	v_rsq_f32_e32 v105, v65
	v_rsq_f32_e32 v106, v66
	v_rsq_f32_e32 v107, v67
	s_waitcnt vmcnt(6)
	v_lshlrev_b32_e32 v108, 16, v72
	v_and_b32_e32 v109, 0xffff0000, v72
	v_lshlrev_b32_e32 v110, 16, v73
	v_and_b32_e32 v111, 0xffff0000, v73
	v_lshlrev_b32_e32 v112, 16, v74
	v_and_b32_e32 v113, 0xffff0000, v74
	v_lshlrev_b32_e32 v114, 16, v75
	v_and_b32_e32 v115, 0xffff0000, v75
	v_mul_f32_e32 v108, v104, v108
	v_mul_f32_e32 v109, v104, v109
	v_mul_f32_e32 v110, v104, v110
	v_mul_f32_e32 v111, v104, v111
	v_mul_f32_e32 v112, v104, v112
	v_mul_f32_e32 v113, v104, v113
	v_mul_f32_e32 v114, v104, v114
	v_mul_f32_e32 v115, v104, v115
	v_mul_f32_e32 v108, v4, v108
	v_mul_f32_e32 v109, v5, v109
	v_mul_f32_e32 v110, v6, v110
	v_mul_f32_e32 v111, v7, v111
	v_mul_f32_e32 v112, v0, v112
	v_mul_f32_e32 v113, v1, v113
	v_mul_f32_e32 v114, v2, v114
	v_mul_f32_e32 v115, v3, v115
	global_store_dwordx4 v[20:21], v[108:111], off
	global_store_dwordx4 v[20:21], v[112:115], off offset:16
	s_nop 1
	v_lshlrev_b32_e32 v108, 16, v76
	v_and_b32_e32 v109, 0xffff0000, v76
	v_lshlrev_b32_e32 v110, 16, v77
	v_and_b32_e32 v111, 0xffff0000, v77
	v_lshlrev_b32_e32 v112, 16, v78
	v_and_b32_e32 v113, 0xffff0000, v78
	v_lshlrev_b32_e32 v114, 16, v79
	v_and_b32_e32 v115, 0xffff0000, v79
	v_mul_f32_e32 v108, v104, v108
	v_mul_f32_e32 v109, v104, v109
	v_mul_f32_e32 v110, v104, v110
	v_mul_f32_e32 v111, v104, v111
	v_mul_f32_e32 v112, v104, v112
	v_mul_f32_e32 v113, v104, v113
	v_mul_f32_e32 v114, v104, v114
	v_mul_f32_e32 v115, v104, v115
	v_mul_f32_e32 v108, v12, v108
	v_mul_f32_e32 v109, v13, v109
	v_mul_f32_e32 v110, v14, v110
	v_mul_f32_e32 v111, v15, v111
	v_mul_f32_e32 v112, v8, v112
	v_mul_f32_e32 v113, v9, v113
	v_mul_f32_e32 v114, v10, v114
	v_mul_f32_e32 v115, v11, v115
	global_store_dwordx4 v[20:21], v[108:111], off offset:2048
	global_store_dwordx4 v[20:21], v[112:115], off offset:2064
	s_nop 1
	v_lshl_add_u64 v[20:21], v[20:21], 0, s[4:5]
	s_waitcnt vmcnt(8)
	v_lshlrev_b32_e32 v108, 16, v80
	v_and_b32_e32 v109, 0xffff0000, v80
	v_lshlrev_b32_e32 v110, 16, v81
	v_and_b32_e32 v111, 0xffff0000, v81
	v_lshlrev_b32_e32 v112, 16, v82
	v_and_b32_e32 v113, 0xffff0000, v82
	v_lshlrev_b32_e32 v114, 16, v83
	v_and_b32_e32 v115, 0xffff0000, v83
	v_mul_f32_e32 v108, v105, v108
	v_mul_f32_e32 v109, v105, v109
	v_mul_f32_e32 v110, v105, v110
	v_mul_f32_e32 v111, v105, v111
	v_mul_f32_e32 v112, v105, v112
	v_mul_f32_e32 v113, v105, v113
	v_mul_f32_e32 v114, v105, v114
	v_mul_f32_e32 v115, v105, v115
	v_mul_f32_e32 v108, v4, v108
	v_mul_f32_e32 v109, v5, v109
	v_mul_f32_e32 v110, v6, v110
	v_mul_f32_e32 v111, v7, v111
	v_mul_f32_e32 v112, v0, v112
	v_mul_f32_e32 v113, v1, v113
	v_mul_f32_e32 v114, v2, v114
	v_mul_f32_e32 v115, v3, v115
	global_store_dwordx4 v[20:21], v[108:111], off
	global_store_dwordx4 v[20:21], v[112:115], off offset:16
	s_nop 1
	v_lshlrev_b32_e32 v108, 16, v84
	v_and_b32_e32 v109, 0xffff0000, v84
	v_lshlrev_b32_e32 v110, 16, v85
	v_and_b32_e32 v111, 0xffff0000, v85
	v_lshlrev_b32_e32 v112, 16, v86
	v_and_b32_e32 v113, 0xffff0000, v86
	v_lshlrev_b32_e32 v114, 16, v87
	v_and_b32_e32 v115, 0xffff0000, v87
	v_mul_f32_e32 v108, v105, v108
	v_mul_f32_e32 v109, v105, v109
	v_mul_f32_e32 v110, v105, v110
	v_mul_f32_e32 v111, v105, v111
	v_mul_f32_e32 v112, v105, v112
	v_mul_f32_e32 v113, v105, v113
	v_mul_f32_e32 v114, v105, v114
	v_mul_f32_e32 v115, v105, v115
	v_mul_f32_e32 v108, v12, v108
	v_mul_f32_e32 v109, v13, v109
	v_mul_f32_e32 v110, v14, v110
	v_mul_f32_e32 v111, v15, v111
	v_mul_f32_e32 v112, v8, v112
	v_mul_f32_e32 v113, v9, v113
	v_mul_f32_e32 v114, v10, v114
	v_mul_f32_e32 v115, v11, v115
	global_store_dwordx4 v[20:21], v[108:111], off offset:2048
	global_store_dwordx4 v[20:21], v[112:115], off offset:2064
	s_nop 1
	v_lshl_add_u64 v[20:21], v[20:21], 0, s[4:5]
	s_waitcnt vmcnt(10)
	v_lshlrev_b32_e32 v108, 16, v88
	v_and_b32_e32 v109, 0xffff0000, v88
	v_lshlrev_b32_e32 v110, 16, v89
	v_and_b32_e32 v111, 0xffff0000, v89
	v_lshlrev_b32_e32 v112, 16, v90
	v_and_b32_e32 v113, 0xffff0000, v90
	v_lshlrev_b32_e32 v114, 16, v91
	v_and_b32_e32 v115, 0xffff0000, v91
	v_mul_f32_e32 v108, v106, v108
	v_mul_f32_e32 v109, v106, v109
	v_mul_f32_e32 v110, v106, v110
	v_mul_f32_e32 v111, v106, v111
	v_mul_f32_e32 v112, v106, v112
	v_mul_f32_e32 v113, v106, v113
	v_mul_f32_e32 v114, v106, v114
	v_mul_f32_e32 v115, v106, v115
	v_mul_f32_e32 v108, v4, v108
	v_mul_f32_e32 v109, v5, v109
	v_mul_f32_e32 v110, v6, v110
	v_mul_f32_e32 v111, v7, v111
	v_mul_f32_e32 v112, v0, v112
	v_mul_f32_e32 v113, v1, v113
	v_mul_f32_e32 v114, v2, v114
	v_mul_f32_e32 v115, v3, v115
	global_store_dwordx4 v[20:21], v[108:111], off
	global_store_dwordx4 v[20:21], v[112:115], off offset:16
	s_nop 1
	v_lshlrev_b32_e32 v108, 16, v92
	v_and_b32_e32 v109, 0xffff0000, v92
	v_lshlrev_b32_e32 v110, 16, v93
	v_and_b32_e32 v111, 0xffff0000, v93
	v_lshlrev_b32_e32 v112, 16, v94
	v_and_b32_e32 v113, 0xffff0000, v94
	v_lshlrev_b32_e32 v114, 16, v95
	v_and_b32_e32 v115, 0xffff0000, v95
	v_mul_f32_e32 v108, v106, v108
	v_mul_f32_e32 v109, v106, v109
	v_mul_f32_e32 v110, v106, v110
	v_mul_f32_e32 v111, v106, v111
	v_mul_f32_e32 v112, v106, v112
	v_mul_f32_e32 v113, v106, v113
	v_mul_f32_e32 v114, v106, v114
	v_mul_f32_e32 v115, v106, v115
	v_mul_f32_e32 v108, v12, v108
	v_mul_f32_e32 v109, v13, v109
	v_mul_f32_e32 v110, v14, v110
	v_mul_f32_e32 v111, v15, v111
	v_mul_f32_e32 v112, v8, v112
	v_mul_f32_e32 v113, v9, v113
	v_mul_f32_e32 v114, v10, v114
	v_mul_f32_e32 v115, v11, v115
	global_store_dwordx4 v[20:21], v[108:111], off offset:2048
	global_store_dwordx4 v[20:21], v[112:115], off offset:2064
	s_nop 1
	v_lshl_add_u64 v[20:21], v[20:21], 0, s[4:5]
	s_waitcnt vmcnt(12)
	v_lshlrev_b32_e32 v108, 16, v96
	v_and_b32_e32 v109, 0xffff0000, v96
	v_lshlrev_b32_e32 v110, 16, v97
	v_and_b32_e32 v111, 0xffff0000, v97
	v_lshlrev_b32_e32 v112, 16, v98
	v_and_b32_e32 v113, 0xffff0000, v98
	v_lshlrev_b32_e32 v114, 16, v99
	v_and_b32_e32 v115, 0xffff0000, v99
	v_mul_f32_e32 v108, v107, v108
	v_mul_f32_e32 v109, v107, v109
	v_mul_f32_e32 v110, v107, v110
	v_mul_f32_e32 v111, v107, v111
	v_mul_f32_e32 v112, v107, v112
	v_mul_f32_e32 v113, v107, v113
	v_mul_f32_e32 v114, v107, v114
	v_mul_f32_e32 v115, v107, v115
	v_mul_f32_e32 v108, v4, v108
	v_mul_f32_e32 v109, v5, v109
	v_mul_f32_e32 v110, v6, v110
	v_mul_f32_e32 v111, v7, v111
	v_mul_f32_e32 v112, v0, v112
	v_mul_f32_e32 v113, v1, v113
	v_mul_f32_e32 v114, v2, v114
	v_mul_f32_e32 v115, v3, v115
	global_store_dwordx4 v[20:21], v[108:111], off
	global_store_dwordx4 v[20:21], v[112:115], off offset:16
	s_nop 1
	v_lshlrev_b32_e32 v108, 16, v100
	v_and_b32_e32 v109, 0xffff0000, v100
	v_lshlrev_b32_e32 v110, 16, v101
	v_and_b32_e32 v111, 0xffff0000, v101
	v_lshlrev_b32_e32 v112, 16, v102
	v_and_b32_e32 v113, 0xffff0000, v102
	v_lshlrev_b32_e32 v114, 16, v103
	v_and_b32_e32 v115, 0xffff0000, v103
	v_mul_f32_e32 v108, v107, v108
	v_mul_f32_e32 v109, v107, v109
	v_mul_f32_e32 v110, v107, v110
	v_mul_f32_e32 v111, v107, v111
	v_mul_f32_e32 v112, v107, v112
	v_mul_f32_e32 v113, v107, v113
	v_mul_f32_e32 v114, v107, v114
	v_mul_f32_e32 v115, v107, v115
	v_mul_f32_e32 v108, v12, v108
	v_mul_f32_e32 v109, v13, v109
	v_mul_f32_e32 v110, v14, v110
	v_mul_f32_e32 v111, v15, v111
	v_mul_f32_e32 v112, v8, v112
	v_mul_f32_e32 v113, v9, v113
	v_mul_f32_e32 v114, v10, v114
	v_mul_f32_e32 v115, v11, v115
	global_store_dwordx4 v[20:21], v[108:111], off offset:2048
	global_store_dwordx4 v[20:21], v[112:115], off offset:2064
	s_nop 1
	v_lshl_add_u64 v[20:21], v[20:21], 0, s[4:5]
	s_lshl_b32 s0, s12, 2
	s_add_i32 s10, s10, s0
	s_cmp_lt_i32 s10, 0x8000
	s_cbranch_scc1 .Lfn_head
